# in-proj K-loop: 4-read LDS fragments issued one phase earlier so every phase issues 4 or 8 ds_read_b128 (was 12/4/8/0), with counted vmcnt waits at ph3/ph7
# baseline (speedup 1.0000x reference)
.LBB0_237:
	s_ashr_i32 s9, s8, 31
	s_lshl_b64 s[10:11], s[8:9], 19
	s_add_u32 s10, s49, s10
	s_addc_u32 s11, s52, s11
	s_ashr_i32 s7, s6, 31
	s_lshl_b64 s[12:13], s[6:7], 19
	s_add_u32 s12, s20, s12
	s_addc_u32 s13, s21, s13
	s_andn2_b64 vcc, exec, s[0:1]
	s_cbranch_vccnz .Lzk_2
	v_mov_b64_e32 v[2:3], 0xc00
	v_cmp_lt_i64_e32 vcc, s[18:19], v[2:3]
	s_and_b64 s[18:19], vcc, exec
	s_cselect_b32 s7, s11, s15
	s_cselect_b32 s9, s10, s14
	s_cselect_b32 s37, s13, s17
	s_cselect_b32 s38, s12, s16
	s_add_u32 s14, s14, 0x40080
	s_addc_u32 s15, s15, 0
	s_add_u32 s39, s16, 0x100
	v_mov_b32_e32 v2, 0
	v_mov_b32_e32 v218, 0xff800000
	v_mov_b32_e32 v155, 0xffffff80
	s_addc_u32 s40, s17, 0
	s_mov_b32 s16, 0
	v_mov_b32_e32 v3, v2
	v_mov_b32_e32 v4, v2
	v_mov_b32_e32 v5, v2
	v_mov_b32_e32 v6, v2
	v_mov_b32_e32 v7, v2
	v_mov_b32_e32 v8, v2
	v_mov_b32_e32 v9, v2
	v_mov_b32_e32 v22, v2
	v_mov_b32_e32 v23, v2
	v_mov_b32_e32 v24, v2
	v_mov_b32_e32 v25, v2
	v_mov_b32_e32 v18, v2
	v_mov_b32_e32 v19, v2
	v_mov_b32_e32 v20, v2
	v_mov_b32_e32 v21, v2
	v_mov_b32_e32 v38, v2
	v_mov_b32_e32 v39, v2
	v_mov_b32_e32 v40, v2
	v_mov_b32_e32 v41, v2
	v_mov_b32_e32 v34, v2
	v_mov_b32_e32 v35, v2
	v_mov_b32_e32 v36, v2
	v_mov_b32_e32 v37, v2
	v_mov_b32_e32 v54, v2
	v_mov_b32_e32 v55, v2
	v_mov_b32_e32 v56, v2
	v_mov_b32_e32 v57, v2
	v_mov_b32_e32 v50, v2
	v_mov_b32_e32 v51, v2
	v_mov_b32_e32 v52, v2
	v_mov_b32_e32 v53, v2
	v_mov_b32_e32 v14, v2
	v_mov_b32_e32 v15, v2
	v_mov_b32_e32 v16, v2
	v_mov_b32_e32 v17, v2
	v_mov_b32_e32 v10, v2
	v_mov_b32_e32 v11, v2
	v_mov_b32_e32 v12, v2
	v_mov_b32_e32 v13, v2
	v_mov_b32_e32 v30, v2
	v_mov_b32_e32 v31, v2
	v_mov_b32_e32 v32, v2
	v_mov_b32_e32 v33, v2
	v_mov_b32_e32 v26, v2
	v_mov_b32_e32 v27, v2
	v_mov_b32_e32 v28, v2
	v_mov_b32_e32 v29, v2
	v_mov_b32_e32 v46, v2
	v_mov_b32_e32 v47, v2
	v_mov_b32_e32 v48, v2
	v_mov_b32_e32 v49, v2
	v_mov_b32_e32 v42, v2
	v_mov_b32_e32 v43, v2
	v_mov_b32_e32 v44, v2
	v_mov_b32_e32 v45, v2
	v_mov_b32_e32 v62, v2
	v_mov_b32_e32 v63, v2
	v_mov_b32_e32 v64, v2
	v_mov_b32_e32 v65, v2
	v_mov_b32_e32 v58, v2
	v_mov_b32_e32 v59, v2
	v_mov_b32_e32 v60, v2
	v_mov_b32_e32 v61, v2
	v_mov_b32_e32 v70, v2
	v_mov_b32_e32 v71, v2
	v_mov_b32_e32 v72, v2
	v_mov_b32_e32 v73, v2
	v_mov_b32_e32 v66, v2
	v_mov_b32_e32 v67, v2
	v_mov_b32_e32 v68, v2
	v_mov_b32_e32 v69, v2
	v_mov_b32_e32 v86, v2
	v_mov_b32_e32 v87, v2
	v_mov_b32_e32 v88, v2
	v_mov_b32_e32 v89, v2
	v_mov_b32_e32 v82, v2
	v_mov_b32_e32 v83, v2
	v_mov_b32_e32 v84, v2
	v_mov_b32_e32 v85, v2
	v_mov_b32_e32 v102, v2
	v_mov_b32_e32 v103, v2
	v_mov_b32_e32 v104, v2
	v_mov_b32_e32 v105, v2
	v_mov_b32_e32 v98, v2
	v_mov_b32_e32 v99, v2
	v_mov_b32_e32 v100, v2
	v_mov_b32_e32 v101, v2
	v_mov_b32_e32 v118, v2
	v_mov_b32_e32 v119, v2
	v_mov_b32_e32 v120, v2
	v_mov_b32_e32 v121, v2
	v_mov_b32_e32 v114, v2
	v_mov_b32_e32 v115, v2
	v_mov_b32_e32 v116, v2
	v_mov_b32_e32 v117, v2
	v_mov_b32_e32 v78, v2
	v_mov_b32_e32 v79, v2
	v_mov_b32_e32 v80, v2
	v_mov_b32_e32 v81, v2
	v_mov_b32_e32 v74, v2
	v_mov_b32_e32 v75, v2
	v_mov_b32_e32 v76, v2
	v_mov_b32_e32 v77, v2
	v_mov_b32_e32 v94, v2
	v_mov_b32_e32 v95, v2
	v_mov_b32_e32 v96, v2
	v_mov_b32_e32 v97, v2
	v_mov_b32_e32 v90, v2
	v_mov_b32_e32 v91, v2
	v_mov_b32_e32 v92, v2
	v_mov_b32_e32 v93, v2
	v_mov_b32_e32 v110, v2
	v_mov_b32_e32 v111, v2
	v_mov_b32_e32 v112, v2
	v_mov_b32_e32 v113, v2
	v_mov_b32_e32 v106, v2
	v_mov_b32_e32 v107, v2
	v_mov_b32_e32 v108, v2
	v_mov_b32_e32 v109, v2
	v_mov_b32_e32 v126, v2
	v_mov_b32_e32 v127, v2
	v_mov_b32_e32 v128, v2
	v_mov_b32_e32 v129, v2
	v_mov_b32_e32 v122, v2
	v_mov_b32_e32 v123, v2
	v_mov_b32_e32 v124, v2
	v_mov_b32_e32 v125, v2
	s_mov_b64 s[74:75], 0x80
	v_add_u32_e32 v149, 0x10000, v1
	ds_read_b128 v[156:159], v149
	ds_read_b128 v[160:163], v149 offset:1024
	ds_read_b128 v[164:167], v149 offset:2048
	ds_read_b128 v[168:171], v149 offset:3072
.LBB0_239:
	s_add_i32 s41, s16, 2
	s_add_u32 s17, s14, 0xfffc0080
	s_addc_u32 s18, s15, -1
	s_add_i32 s42, 0, 0x10000
	s_cmp_eq_u32 s31, s16
	s_cselect_b32 s16, s38, s39
	s_cselect_b32 s19, s7, s18
	s_cselect_b32 s18, s9, s17
	s_cselect_b32 s17, s37, s40
	v_lshl_add_u64 v[204:205], s[14:15], 0, v[140:141]
	s_add_i32 m0, s23, 0xc000
	ds_read_b128 v[172:175], v151
	ds_read_b128 v[176:179], v151 offset:1024
	ds_read_b128 v[180:183], v151 offset:2048
	ds_read_b128 v[184:187], v151 offset:3072
	ds_read_b128 v[188:191], v151 offset:4096
	ds_read_b128 v[192:195], v151 offset:5120
	ds_read_b128 v[196:199], v151 offset:6144
	ds_read_b128 v[200:203], v151 offset:7168
	global_load_lds_dwordx4 v[204:205], off
	v_lshl_add_u64 v[204:205], s[14:15], 0, v[142:143]
	s_add_i32 m0, s23, 0xe000
	s_nop 0
	global_load_lds_dwordx4 v[204:205], off
	s_waitcnt lgkmcnt(8)
	s_barrier
	s_waitcnt lgkmcnt(0)
	s_setprio 1
	s_waitcnt lgkmcnt(0)
	v_mfma_f32_16x16x32_bf16 v[122:125], v[156:159], v[172:175], v[122:125]
	v_mfma_f32_16x16x32_bf16 v[126:129], v[164:167], v[172:175], v[126:129]
	v_mfma_f32_16x16x32_bf16 v[106:109], v[156:159], v[180:183], v[106:109]
	v_mfma_f32_16x16x32_bf16 v[110:113], v[164:167], v[180:183], v[110:113]
	v_mfma_f32_16x16x32_bf16 v[90:93], v[156:159], v[188:191], v[90:93]
	v_mfma_f32_16x16x32_bf16 v[94:97], v[164:167], v[188:191], v[94:97]
	v_mfma_f32_16x16x32_bf16 v[74:77], v[156:159], v[196:199], v[74:77]
	v_mfma_f32_16x16x32_bf16 v[78:81], v[164:167], v[196:199], v[78:81]
	v_mfma_f32_16x16x32_bf16 v[122:125], v[160:163], v[176:179], v[122:125]
	v_mfma_f32_16x16x32_bf16 v[126:129], v[168:171], v[176:179], v[126:129]
	v_mfma_f32_16x16x32_bf16 v[106:109], v[160:163], v[184:187], v[106:109]
	v_mfma_f32_16x16x32_bf16 v[110:113], v[168:171], v[184:187], v[110:113]
	v_mfma_f32_16x16x32_bf16 v[90:93], v[160:163], v[192:195], v[90:93]
	v_mfma_f32_16x16x32_bf16 v[94:97], v[168:171], v[192:195], v[94:97]
	v_mfma_f32_16x16x32_bf16 v[74:77], v[160:163], v[200:203], v[74:77]
	v_mfma_f32_16x16x32_bf16 v[78:81], v[168:171], v[200:203], v[78:81]
	s_setprio 0
	s_barrier
	s_add_i32 s44, 0, 0x14000
	s_add_i32 s42, s42, s22
	v_add_u32_e32 v149, s44, v1
	v_lshl_add_u64 v[230:231], s[16:17], 0, v[134:135]
	s_mov_b32 m0, s42
	ds_read_b128 v[204:207], v149
	ds_read_b128 v[208:211], v149 offset:1024
	ds_read_b128 v[212:215], v149 offset:2048
	ds_read_b128 v[226:229], v149 offset:3072
	global_load_lds_dwordx4 v[230:231], off
	v_lshl_add_u64 v[232:233], s[16:17], 0, v[130:131]
	s_add_i32 m0, s42, 0x2000
	s_nop 0
	global_load_lds_dwordx4 v[232:233], off
	s_barrier
	s_waitcnt lgkmcnt(0)
	s_setprio 1
	s_waitcnt lgkmcnt(0)
	v_mfma_f32_16x16x32_bf16 v[114:117], v[204:207], v[172:175], v[114:117]
	v_mfma_f32_16x16x32_bf16 v[118:121], v[212:215], v[172:175], v[118:121]
	v_mfma_f32_16x16x32_bf16 v[98:101], v[204:207], v[180:183], v[98:101]
	v_mfma_f32_16x16x32_bf16 v[102:105], v[212:215], v[180:183], v[102:105]
	v_mfma_f32_16x16x32_bf16 v[82:85], v[204:207], v[188:191], v[82:85]
	v_mfma_f32_16x16x32_bf16 v[86:89], v[212:215], v[188:191], v[86:89]
	v_mfma_f32_16x16x32_bf16 v[66:69], v[204:207], v[196:199], v[66:69]
	v_mfma_f32_16x16x32_bf16 v[70:73], v[212:215], v[196:199], v[70:73]
	v_mfma_f32_16x16x32_bf16 v[114:117], v[208:211], v[176:179], v[114:117]
	v_mfma_f32_16x16x32_bf16 v[118:121], v[226:229], v[176:179], v[118:121]
	v_mfma_f32_16x16x32_bf16 v[98:101], v[208:211], v[184:187], v[98:101]
	v_mfma_f32_16x16x32_bf16 v[102:105], v[226:229], v[184:187], v[102:105]
	v_mfma_f32_16x16x32_bf16 v[82:85], v[208:211], v[192:195], v[82:85]
	v_mfma_f32_16x16x32_bf16 v[86:89], v[226:229], v[192:195], v[86:89]
	v_mfma_f32_16x16x32_bf16 v[66:69], v[208:211], v[200:203], v[66:69]
	v_mfma_f32_16x16x32_bf16 v[70:73], v[226:229], v[200:203], v[70:73]
	s_setprio 0
	s_mov_b32 m0, s23
	v_lshl_add_u64 v[234:235], s[18:19], 0, v[136:137]
	s_barrier
	ds_read_b128 v[172:175], v151 offset:16384
	ds_read_b128 v[176:179], v151 offset:17408
	ds_read_b128 v[180:183], v151 offset:18432
	ds_read_b128 v[184:187], v151 offset:19456
	ds_read_b128 v[188:191], v151 offset:20480
	ds_read_b128 v[192:195], v151 offset:21504
	ds_read_b128 v[196:199], v151 offset:22528
	ds_read_b128 v[200:203], v151 offset:23552
	global_load_lds_dwordx4 v[234:235], off
	v_lshl_add_u64 v[236:237], s[18:19], 0, v[132:133]
	s_mov_b32 m0, s24
	s_nop 0
	global_load_lds_dwordx4 v[236:237], off
	s_cmp_eq_u32 s100, 0
	s_cbranch_scc1 .Lip_w3n
	s_waitcnt vmcnt(22)
	s_branch .Lip_w3d
.Lip_w3n:
	s_waitcnt vmcnt(10)
.Lip_w3d:
	s_barrier
	s_waitcnt lgkmcnt(0)
	s_setprio 1
	s_waitcnt lgkmcnt(0)
	v_mfma_f32_16x16x32_bf16 v[58:61], v[156:159], v[172:175], v[58:61]
	v_mfma_f32_16x16x32_bf16 v[62:65], v[164:167], v[172:175], v[62:65]
	v_mfma_f32_16x16x32_bf16 v[42:45], v[156:159], v[180:183], v[42:45]
	v_mfma_f32_16x16x32_bf16 v[46:49], v[164:167], v[180:183], v[46:49]
	v_mfma_f32_16x16x32_bf16 v[26:29], v[156:159], v[188:191], v[26:29]
	v_mfma_f32_16x16x32_bf16 v[30:33], v[164:167], v[188:191], v[30:33]
	v_mfma_f32_16x16x32_bf16 v[10:13], v[156:159], v[196:199], v[10:13]
	v_mfma_f32_16x16x32_bf16 v[14:17], v[164:167], v[196:199], v[14:17]
	v_mfma_f32_16x16x32_bf16 v[58:61], v[160:163], v[176:179], v[58:61]
	v_mfma_f32_16x16x32_bf16 v[62:65], v[168:171], v[176:179], v[62:65]
	v_mfma_f32_16x16x32_bf16 v[42:45], v[160:163], v[184:187], v[42:45]
	v_mfma_f32_16x16x32_bf16 v[46:49], v[168:171], v[184:187], v[46:49]
	v_mfma_f32_16x16x32_bf16 v[26:29], v[160:163], v[192:195], v[26:29]
	v_mfma_f32_16x16x32_bf16 v[30:33], v[168:171], v[192:195], v[30:33]
	v_mfma_f32_16x16x32_bf16 v[10:13], v[160:163], v[200:203], v[10:13]
	v_mfma_f32_16x16x32_bf16 v[14:17], v[168:171], v[200:203], v[14:17]
	s_setprio 0
	s_barrier
	s_add_u32 s42, s16, 0x40000
	s_addc_u32 s43, s17, 0
	s_add_i32 s44, s44, s22
	v_lshl_add_u64 v[156:157], s[42:43], 0, v[134:135]
	s_mov_b32 m0, s44
	s_nop 0
	global_load_lds_dwordx4 v[156:157], off
	v_lshl_add_u64 v[156:157], s[42:43], 0, v[130:131]
	s_add_i32 m0, s44, 0x2000
	s_nop 0
	global_load_lds_dwordx4 v[156:157], off
	v_add_u32_e32 v149, 0x18000, v1
	ds_read_b128 v[156:159], v149
	ds_read_b128 v[160:163], v149 offset:1024
	ds_read_b128 v[164:167], v149 offset:2048
	ds_read_b128 v[168:171], v149 offset:3072
	s_cmp_eq_u32 s100, 0
	s_cbranch_scc1 .Lip_w4n
	s_waitcnt vmcnt(24)
	s_branch .Lip_w4d

.Lip_w4d:
	s_barrier
	s_setprio 1
	v_mfma_f32_16x16x32_bf16 v[50:53], v[204:207], v[172:175], v[50:53]
	v_mfma_f32_16x16x32_bf16 v[54:57], v[212:215], v[172:175], v[54:57]
	v_mfma_f32_16x16x32_bf16 v[34:37], v[204:207], v[180:183], v[34:37]
	v_mfma_f32_16x16x32_bf16 v[38:41], v[212:215], v[180:183], v[38:41]
	v_mfma_f32_16x16x32_bf16 v[18:21], v[204:207], v[188:191], v[18:21]
	v_mfma_f32_16x16x32_bf16 v[22:25], v[212:215], v[188:191], v[22:25]
	v_mfma_f32_16x16x32_bf16 v[6:9], v[204:207], v[196:199], v[6:9]
	v_mfma_f32_16x16x32_bf16 v[2:5], v[212:215], v[196:199], v[2:5]
	v_mfma_f32_16x16x32_bf16 v[50:53], v[208:211], v[176:179], v[50:53]
	v_mfma_f32_16x16x32_bf16 v[54:57], v[226:229], v[176:179], v[54:57]
	v_mfma_f32_16x16x32_bf16 v[34:37], v[208:211], v[184:187], v[34:37]
	v_mfma_f32_16x16x32_bf16 v[38:41], v[226:229], v[184:187], v[38:41]
	v_mfma_f32_16x16x32_bf16 v[18:21], v[208:211], v[192:195], v[18:21]
	v_mfma_f32_16x16x32_bf16 v[22:25], v[226:229], v[192:195], v[22:25]
	v_mfma_f32_16x16x32_bf16 v[6:9], v[208:211], v[200:203], v[6:9]
	v_mfma_f32_16x16x32_bf16 v[2:5], v[226:229], v[200:203], v[2:5]
	s_setprio 0
	s_add_i32 s42, 0, 0x18000
	s_barrier
	s_add_u32 s18, s18, 0x40000
	s_addc_u32 s19, s19, 0
	s_mov_b32 m0, s25
	v_lshl_add_u64 v[204:205], s[18:19], 0, v[136:137]
	ds_read_b128 v[172:175], v151 offset:32768
	ds_read_b128 v[176:179], v151 offset:33792
	ds_read_b128 v[180:183], v151 offset:34816
	ds_read_b128 v[184:187], v151 offset:35840
	ds_read_b128 v[188:191], v151 offset:36864
	ds_read_b128 v[192:195], v151 offset:37888
	ds_read_b128 v[196:199], v151 offset:38912
	ds_read_b128 v[200:203], v151 offset:39936
	global_load_lds_dwordx4 v[204:205], off
	v_lshl_add_u64 v[204:205], s[18:19], 0, v[132:133]
	s_mov_b32 m0, s26
	s_nop 0
	global_load_lds_dwordx4 v[204:205], off
	s_waitcnt lgkmcnt(8)
	s_barrier
	s_waitcnt lgkmcnt(0)
	s_setprio 1
	s_waitcnt lgkmcnt(0)
	v_mfma_f32_16x16x32_bf16 v[122:125], v[156:159], v[172:175], v[122:125]
	v_mfma_f32_16x16x32_bf16 v[126:129], v[164:167], v[172:175], v[126:129]
	v_mfma_f32_16x16x32_bf16 v[106:109], v[156:159], v[180:183], v[106:109]
	v_mfma_f32_16x16x32_bf16 v[110:113], v[164:167], v[180:183], v[110:113]
	v_mfma_f32_16x16x32_bf16 v[90:93], v[156:159], v[188:191], v[90:93]
	v_mfma_f32_16x16x32_bf16 v[94:97], v[164:167], v[188:191], v[94:97]
	v_mfma_f32_16x16x32_bf16 v[74:77], v[156:159], v[196:199], v[74:77]
	v_mfma_f32_16x16x32_bf16 v[78:81], v[164:167], v[196:199], v[78:81]
	v_mfma_f32_16x16x32_bf16 v[122:125], v[160:163], v[176:179], v[122:125]
	v_mfma_f32_16x16x32_bf16 v[126:129], v[168:171], v[176:179], v[126:129]
	v_mfma_f32_16x16x32_bf16 v[106:109], v[160:163], v[184:187], v[106:109]
	v_mfma_f32_16x16x32_bf16 v[110:113], v[168:171], v[184:187], v[110:113]
	v_mfma_f32_16x16x32_bf16 v[90:93], v[160:163], v[192:195], v[90:93]
	v_mfma_f32_16x16x32_bf16 v[94:97], v[168:171], v[192:195], v[94:97]
	v_mfma_f32_16x16x32_bf16 v[74:77], v[160:163], v[200:203], v[74:77]
	v_mfma_f32_16x16x32_bf16 v[78:81], v[168:171], v[200:203], v[78:81]
	s_setprio 0
	s_barrier
	s_add_i32 s18, 0, 0x1c000
	s_add_i32 s19, s42, s22
	v_add_u32_e32 v149, s18, v1
	v_lshl_add_u64 v[230:231], v[230:231], 0, s[74:75]
	s_mov_b32 m0, s19
	ds_read_b128 v[204:207], v149
	ds_read_b128 v[208:211], v149 offset:1024
	ds_read_b128 v[212:215], v149 offset:2048
	ds_read_b128 v[226:229], v149 offset:3072
	global_load_lds_dwordx4 v[230:231], off
	v_lshl_add_u64 v[230:231], v[232:233], 0, s[74:75]
	s_add_i32 m0, s19, 0x2000
	s_nop 0
	global_load_lds_dwordx4 v[230:231], off
	s_cmp_eq_u32 s100, 0
	s_cbranch_scc1 .Lip_w6n
	s_waitcnt vmcnt(10)
	s_mov_b32 s100, 0
.Lip_w6n:
	s_barrier
	s_waitcnt lgkmcnt(0)
	s_setprio 1
	s_waitcnt lgkmcnt(0)
	v_mfma_f32_16x16x32_bf16 v[114:117], v[204:207], v[172:175], v[114:117]
	v_mfma_f32_16x16x32_bf16 v[118:121], v[212:215], v[172:175], v[118:121]
	v_mfma_f32_16x16x32_bf16 v[98:101], v[204:207], v[180:183], v[98:101]
	v_mfma_f32_16x16x32_bf16 v[102:105], v[212:215], v[180:183], v[102:105]
	v_mfma_f32_16x16x32_bf16 v[82:85], v[204:207], v[188:191], v[82:85]
	v_mfma_f32_16x16x32_bf16 v[86:89], v[212:215], v[188:191], v[86:89]
	v_mfma_f32_16x16x32_bf16 v[66:69], v[204:207], v[196:199], v[66:69]
	v_mfma_f32_16x16x32_bf16 v[70:73], v[212:215], v[196:199], v[70:73]
	v_mfma_f32_16x16x32_bf16 v[114:117], v[208:211], v[176:179], v[114:117]
	v_mfma_f32_16x16x32_bf16 v[118:121], v[226:229], v[176:179], v[118:121]
	v_mfma_f32_16x16x32_bf16 v[98:101], v[208:211], v[184:187], v[98:101]
	v_mfma_f32_16x16x32_bf16 v[102:105], v[226:229], v[184:187], v[102:105]
	v_mfma_f32_16x16x32_bf16 v[82:85], v[208:211], v[192:195], v[82:85]
	v_mfma_f32_16x16x32_bf16 v[86:89], v[226:229], v[192:195], v[86:89]
	v_mfma_f32_16x16x32_bf16 v[66:69], v[208:211], v[200:203], v[66:69]
	v_mfma_f32_16x16x32_bf16 v[70:73], v[226:229], v[200:203], v[70:73]
	s_setprio 0
	s_mov_b32 m0, s28
	v_lshl_add_u64 v[230:231], v[234:235], 0, s[74:75]
	s_barrier
	ds_read_b128 v[172:175], v151 offset:49152
	ds_read_b128 v[176:179], v151 offset:50176
	ds_read_b128 v[180:183], v151 offset:51200
	ds_read_b128 v[184:187], v151 offset:52224
	ds_read_b128 v[188:191], v151 offset:53248
	ds_read_b128 v[192:195], v151 offset:54272
	ds_read_b128 v[196:199], v151 offset:55296
	ds_read_b128 v[200:203], v151 offset:56320
	global_load_lds_dwordx4 v[230:231], off
	v_lshl_add_u64 v[230:231], v[236:237], 0, s[74:75]
	s_mov_b32 m0, s29
	s_nop 0
	global_load_lds_dwordx4 v[230:231], off
	s_waitcnt vmcnt(10)
	s_barrier
	s_waitcnt lgkmcnt(0)
	s_setprio 1
	s_waitcnt lgkmcnt(0)
	v_mfma_f32_16x16x32_bf16 v[58:61], v[156:159], v[172:175], v[58:61]
	v_mfma_f32_16x16x32_bf16 v[62:65], v[164:167], v[172:175], v[62:65]
	v_mfma_f32_16x16x32_bf16 v[42:45], v[156:159], v[180:183], v[42:45]
	v_mfma_f32_16x16x32_bf16 v[46:49], v[164:167], v[180:183], v[46:49]
	v_mfma_f32_16x16x32_bf16 v[26:29], v[156:159], v[188:191], v[26:29]
	v_mfma_f32_16x16x32_bf16 v[30:33], v[164:167], v[188:191], v[30:33]
	v_mfma_f32_16x16x32_bf16 v[10:13], v[156:159], v[196:199], v[10:13]
	v_mfma_f32_16x16x32_bf16 v[14:17], v[164:167], v[196:199], v[14:17]
	v_mfma_f32_16x16x32_bf16 v[58:61], v[160:163], v[176:179], v[58:61]
	v_mfma_f32_16x16x32_bf16 v[62:65], v[168:171], v[176:179], v[62:65]
	v_mfma_f32_16x16x32_bf16 v[42:45], v[160:163], v[184:187], v[42:45]
	v_mfma_f32_16x16x32_bf16 v[46:49], v[168:171], v[184:187], v[46:49]
	v_mfma_f32_16x16x32_bf16 v[26:29], v[160:163], v[192:195], v[26:29]
	v_mfma_f32_16x16x32_bf16 v[30:33], v[168:171], v[192:195], v[30:33]
	v_mfma_f32_16x16x32_bf16 v[10:13], v[160:163], v[200:203], v[10:13]
	v_mfma_f32_16x16x32_bf16 v[14:17], v[168:171], v[200:203], v[14:17]
	s_setprio 0
	s_barrier
	s_add_u32 s16, s16, 0x40080
	s_addc_u32 s17, s17, 0
	s_add_i32 s18, s18, s22
	v_lshl_add_u64 v[156:157], s[16:17], 0, v[134:135]
	s_mov_b32 m0, s18
	s_nop 0
	global_load_lds_dwordx4 v[156:157], off
	v_lshl_add_u64 v[156:157], s[16:17], 0, v[130:131]
	s_add_i32 m0, s18, 0x2000
	s_nop 0
	global_load_lds_dwordx4 v[156:157], off
	v_add_u32_e32 v149, 0x10000, v1
	ds_read_b128 v[156:159], v149
	ds_read_b128 v[160:163], v149 offset:1024
	ds_read_b128 v[164:167], v149 offset:2048
	ds_read_b128 v[168:171], v149 offset:3072
	s_waitcnt vmcnt(6)
	s_barrier
	s_setprio 1
	v_mfma_f32_16x16x32_bf16 v[50:53], v[204:207], v[172:175], v[50:53]
	v_mfma_f32_16x16x32_bf16 v[54:57], v[212:215], v[172:175], v[54:57]
	v_mfma_f32_16x16x32_bf16 v[34:37], v[204:207], v[180:183], v[34:37]
	v_mfma_f32_16x16x32_bf16 v[38:41], v[212:215], v[180:183], v[38:41]
	v_mfma_f32_16x16x32_bf16 v[18:21], v[204:207], v[188:191], v[18:21]
	v_mfma_f32_16x16x32_bf16 v[22:25], v[212:215], v[188:191], v[22:25]
	v_mfma_f32_16x16x32_bf16 v[6:9], v[204:207], v[196:199], v[6:9]
	v_mfma_f32_16x16x32_bf16 v[2:5], v[212:215], v[196:199], v[2:5]
	v_mfma_f32_16x16x32_bf16 v[50:53], v[208:211], v[176:179], v[50:53]
	v_mfma_f32_16x16x32_bf16 v[54:57], v[226:229], v[176:179], v[54:57]
	v_mfma_f32_16x16x32_bf16 v[34:37], v[208:211], v[184:187], v[34:37]
	v_mfma_f32_16x16x32_bf16 v[38:41], v[226:229], v[184:187], v[38:41]
	v_mfma_f32_16x16x32_bf16 v[18:21], v[208:211], v[192:195], v[18:21]
	v_mfma_f32_16x16x32_bf16 v[22:25], v[226:229], v[192:195], v[22:25]
	v_mfma_f32_16x16x32_bf16 v[6:9], v[208:211], v[200:203], v[6:9]
	v_mfma_f32_16x16x32_bf16 v[2:5], v[226:229], v[200:203], v[2:5]
	s_setprio 0
	s_add_u32 s14, s14, 0x100
	s_addc_u32 s15, s15, 0
	s_add_u32 s39, s39, 0x100
	s_addc_u32 s40, s40, 0
	s_cmp_ge_i32 s41, s27
	s_mov_b32 s16, s41
	s_barrier
	s_cbranch_scc0 .LBB0_239
	s_waitcnt lgkmcnt(0)
	v_readlane_b32 s38, v255, 8
	v_mov_b32_e32 v203, v155
	v_readlane_b32 s39, v255, 9
	s_cmp_lt_i32 s35, 32
	s_mov_b64 s[14:15], -1
	s_cbranch_scc1 .LBB0_243
